# v22 plus removal of compiler false-hazard s_nop 0 between dependent v_pk_fma_f32 in the PEER gather loops
# speedup vs baseline: 1.0066x; 1.0066x over previous
.LBB0_1641:
	s_waitcnt vmcnt(1)
	ds_bpermute_b32 v32, v156, v176
	ds_bpermute_b32 v33, v158, v176
	ds_bpermute_b32 v38, v159, v176
	ds_bpermute_b32 v39, v160, v176
	ds_bpermute_b32 v40, v161, v176
	s_waitcnt lgkmcnt(4)
	v_lshlrev_b32_e32 v0, 7, v32
	v_and_b32_e32 v0, 0x7fff80, v0
	v_lshl_add_u64 v[30:31], v[134:135], 0, v[0:1]
	v_lshlrev_b32_sdwa v0, v231, v32 dst_sel:DWORD dst_unused:UNUSED_PAD src0_sel:DWORD src1_sel:WORD_1
	global_load_dwordx4 v[126:129], v[30:31], off
	v_lshl_add_u64 v[30:31], v[134:135], 0, v[0:1]
	s_waitcnt lgkmcnt(3)
	v_lshlrev_b32_e32 v0, 7, v33
	v_and_b32_e32 v0, 0x7fff80, v0
	global_load_dwordx4 v[122:125], v[30:31], off
	v_lshl_add_u64 v[30:31], v[134:135], 0, v[0:1]
	v_lshlrev_b32_sdwa v0, v231, v33 dst_sel:DWORD dst_unused:UNUSED_PAD src0_sel:DWORD src1_sel:WORD_1
	global_load_dwordx4 v[118:121], v[30:31], off
	v_lshl_add_u64 v[30:31], v[134:135], 0, v[0:1]
	s_waitcnt lgkmcnt(2)
	v_lshlrev_b32_e32 v0, 7, v38
	v_and_b32_e32 v0, 0x7fff80, v0
	global_load_dwordx4 v[114:117], v[30:31], off
	v_lshl_add_u64 v[30:31], v[134:135], 0, v[0:1]
	v_lshlrev_b32_sdwa v0, v231, v38 dst_sel:DWORD dst_unused:UNUSED_PAD src0_sel:DWORD src1_sel:WORD_1
	global_load_dwordx4 v[110:113], v[30:31], off
	v_lshl_add_u64 v[30:31], v[134:135], 0, v[0:1]
	s_waitcnt lgkmcnt(1)
	v_lshlrev_b32_e32 v0, 7, v39
	ds_bpermute_b32 v41, v162, v176
	v_and_b32_e32 v0, 0x7fff80, v0
	global_load_dwordx4 v[102:105], v[30:31], off
	v_lshl_add_u64 v[30:31], v[134:135], 0, v[0:1]
	v_lshlrev_b32_sdwa v0, v231, v39 dst_sel:DWORD dst_unused:UNUSED_PAD src0_sel:DWORD src1_sel:WORD_1
	global_load_dwordx4 v[94:97], v[30:31], off
	v_lshl_add_u64 v[30:31], v[134:135], 0, v[0:1]
	s_waitcnt lgkmcnt(1)
	v_lshlrev_b32_e32 v0, 7, v40
	ds_bpermute_b32 v46, v163, v176
	v_and_b32_e32 v0, 0x7fff80, v0
	global_load_dwordx4 v[90:93], v[30:31], off
	v_lshl_add_u64 v[30:31], v[134:135], 0, v[0:1]
	v_lshlrev_b32_sdwa v0, v231, v40 dst_sel:DWORD dst_unused:UNUSED_PAD src0_sel:DWORD src1_sel:WORD_1
	global_load_dwordx4 v[82:85], v[30:31], off
	v_lshl_add_u64 v[30:31], v[134:135], 0, v[0:1]
	s_waitcnt lgkmcnt(1)
	v_lshlrev_b32_e32 v0, 7, v41
	ds_bpermute_b32 v140, v164, v176
	v_and_b32_e32 v0, 0x7fff80, v0
	global_load_dwordx4 v[74:77], v[30:31], off
	v_lshl_add_u64 v[30:31], v[134:135], 0, v[0:1]
	v_lshlrev_b32_sdwa v0, v231, v41 dst_sel:DWORD dst_unused:UNUSED_PAD src0_sel:DWORD src1_sel:WORD_1
	global_load_dwordx4 v[66:69], v[30:31], off
	v_lshl_add_u64 v[30:31], v[134:135], 0, v[0:1]
	s_waitcnt lgkmcnt(1)
	v_lshlrev_b32_e32 v0, 7, v46
	v_and_b32_e32 v0, 0x7fff80, v0
	global_load_dwordx4 v[62:65], v[30:31], off
	v_lshl_add_u64 v[30:31], v[134:135], 0, v[0:1]
	v_lshlrev_b32_sdwa v0, v231, v46 dst_sel:DWORD dst_unused:UNUSED_PAD src0_sel:DWORD src1_sel:WORD_1
	v_mov_b32_e32 v174, v157
	global_load_dwordx4 v[54:57], v[30:31], off
	v_lshl_add_u64 v[30:31], v[134:135], 0, v[0:1]
	s_waitcnt lgkmcnt(0)
	v_lshlrev_b32_e32 v0, 7, v140
	v_readlane_b32 s0, v252, 2
	v_and_b32_e32 v0, 0x7fff80, v0
	global_load_dwordx4 v[46:49], v[30:31], off
	v_add_u32_e32 v157, s0, v174
	v_lshl_add_u64 v[30:31], v[134:135], 0, v[0:1]
	v_lshlrev_b32_sdwa v0, v231, v140 dst_sel:DWORD dst_unused:UNUSED_PAD src0_sel:DWORD src1_sel:WORD_1
	v_min_i32_e32 v140, 0x13fff, v157
	v_ashrrev_i32_e32 v141, 31, v140
	v_lshlrev_b64 v[142:143], 11, v[140:141]
	v_lshlrev_b64 v[140:141], 8, v[140:141]
	v_mov_b32_e32 v154, v173
	v_lshl_add_u64 v[140:141], v[132:133], 0, v[140:141]
	global_load_dwordx4 v[38:41], v[30:31], off
	v_lshl_add_u64 v[30:31], v[134:135], 0, v[0:1]
	v_lshl_add_u64 v[142:143], v[130:131], 0, v[142:143]
	global_load_dword v0, v[140:141], off
	ds_bpermute_b32 v141, v165, v154
	global_load_dword v173, v[142:143], off
	ds_bpermute_b32 v142, v166, v154
	v_cvt_pk_f32_fp8_e32 v[176:177], v106
	v_cvt_pk_f32_fp8_sdwa v[178:179], v106 src0_sel:WORD_1
	s_waitcnt lgkmcnt(1)
	v_lshlrev_b32_e32 v140, 16, v141
	v_and_b32_e32 v141, 0xffff0000, v141
	ds_bpermute_b32 v143, v167, v154
	s_waitcnt lgkmcnt(1)
	v_lshlrev_b32_e32 v144, 16, v142
	v_and_b32_e32 v145, 0xffff0000, v142
	ds_bpermute_b32 v147, v168, v154
	v_pk_fma_f32 v[176:177], v[176:177], v[140:141], 0 op_sel_hi:[1,1,0]
	s_waitcnt lgkmcnt(1)
	v_lshlrev_b32_e32 v142, 16, v143
	v_pk_fma_f32 v[176:177], v[178:179], v[144:145], v[176:177]
	v_cvt_pk_f32_fp8_e32 v[178:179], v107
	v_cvt_pk_f32_fp8_sdwa v[106:107], v107 src0_sel:WORD_1
	v_and_b32_e32 v143, 0xffff0000, v143
	ds_bpermute_b32 v149, v169, v154
	s_waitcnt lgkmcnt(1)
	v_lshlrev_b32_e32 v146, 16, v147
	v_and_b32_e32 v147, 0xffff0000, v147
	v_pk_fma_f32 v[176:177], v[178:179], v[142:143], v[176:177]
	ds_bpermute_b32 v150, v170, v154
	v_pk_fma_f32 v[106:107], v[106:107], v[146:147], v[176:177]
	v_cvt_pk_f32_fp8_e32 v[176:177], v108
	ds_bpermute_b32 v151, v171, v154
	s_waitcnt lgkmcnt(2)
	v_lshlrev_b32_e32 v148, 16, v149
	v_and_b32_e32 v149, 0xffff0000, v149
	ds_bpermute_b32 v155, v172, v154
	v_cvt_pk_f32_fp8_sdwa v[178:179], v108 src0_sel:WORD_1
	v_pk_fma_f32 v[106:107], v[176:177], v[148:149], v[106:107]
	v_cvt_pk_f32_fp8_e32 v[176:177], v109
	v_cvt_pk_f32_fp8_sdwa v[108:109], v109 src0_sel:WORD_1
	s_waitcnt lgkmcnt(2)
	v_lshlrev_b32_e32 v152, 16, v150
	v_and_b32_e32 v153, 0xffff0000, v150
	s_waitcnt lgkmcnt(1)
	v_lshlrev_b32_e32 v150, 16, v151
	v_and_b32_e32 v151, 0xffff0000, v151
	v_pk_fma_f32 v[106:107], v[178:179], v[152:153], v[106:107]
	s_waitcnt lgkmcnt(0)
	v_lshlrev_b32_e32 v154, 16, v155
	v_and_b32_e32 v155, 0xffff0000, v155
	v_pk_fma_f32 v[106:107], v[176:177], v[150:151], v[106:107]
	global_load_dwordx4 v[30:33], v[30:31], off
	v_pk_fma_f32 v[106:107], v[108:109], v[154:155], v[106:107]
	v_cvt_pk_f32_fp8_sdwa v[108:109], v98 src0_sel:WORD_1
	v_add_f32_e32 v106, v106, v107
	s_waitcnt vmcnt(17)
	v_cvt_pk_f32_fp8_e32 v[178:179], v126
	v_cvt_pk_f32_fp8_sdwa v[180:181], v126 src0_sel:WORD_1
	v_add_f32_dpp v106, v106, v106 quad_perm:[1,0,3,2] row_mask:0xf bank_mask:0xf bound_ctrl:1
	v_readlane_b32 s1, v252, 3
	s_nop 0
	v_add_f32_dpp v106, v106, v106 quad_perm:[2,3,0,1] row_mask:0xf bank_mask:0xf bound_ctrl:1
	s_nop 1
	v_add_f32_dpp v106, v106, v106 row_half_mirror row_mask:0xf bank_mask:0xf bound_ctrl:1
	v_cndmask_b32_e32 v176, 0, v106, vcc
	v_cvt_pk_f32_fp8_e32 v[106:107], v98
	v_pk_fma_f32 v[106:107], v[106:107], v[140:141], 0 op_sel_hi:[1,1,0]
	v_pk_fma_f32 v[106:107], v[108:109], v[144:145], v[106:107]
	v_cvt_pk_f32_fp8_e32 v[108:109], v99
	v_cvt_pk_f32_fp8_sdwa v[98:99], v99 src0_sel:WORD_1
	v_pk_fma_f32 v[106:107], v[108:109], v[142:143], v[106:107]
	v_pk_fma_f32 v[98:99], v[98:99], v[146:147], v[106:107]
	v_cvt_pk_f32_fp8_e32 v[106:107], v100
	v_cvt_pk_f32_fp8_sdwa v[108:109], v100 src0_sel:WORD_1
	v_pk_fma_f32 v[98:99], v[106:107], v[148:149], v[98:99]
	v_cvt_pk_f32_fp8_e32 v[106:107], v101
	v_cvt_pk_f32_fp8_sdwa v[100:101], v101 src0_sel:WORD_1
	v_pk_fma_f32 v[98:99], v[108:109], v[152:153], v[98:99]
	v_pk_fma_f32 v[98:99], v[106:107], v[150:151], v[98:99]
	v_pk_fma_f32 v[98:99], v[100:101], v[154:155], v[98:99]
	v_cvt_pk_f32_fp8_sdwa v[100:101], v86 src0_sel:WORD_1
	v_add_f32_e32 v98, v98, v99
	s_nop 1
	v_add_f32_dpp v98, v98, v98 quad_perm:[1,0,3,2] row_mask:0xf bank_mask:0xf bound_ctrl:1
	s_nop 1
	v_add_f32_dpp v98, v98, v98 quad_perm:[2,3,0,1] row_mask:0xf bank_mask:0xf bound_ctrl:1
	s_nop 1
	v_add_f32_dpp v98, v98, v98 row_half_mirror row_mask:0xf bank_mask:0xf bound_ctrl:1
	v_cndmask_b32_e64 v106, v176, v98, s[42:43]
	v_cvt_pk_f32_fp8_e32 v[98:99], v86
	v_pk_fma_f32 v[98:99], v[98:99], v[140:141], 0 op_sel_hi:[1,1,0]
	v_pk_fma_f32 v[98:99], v[100:101], v[144:145], v[98:99]
	v_cvt_pk_f32_fp8_e32 v[100:101], v87
	v_cvt_pk_f32_fp8_sdwa v[86:87], v87 src0_sel:WORD_1
	v_pk_fma_f32 v[98:99], v[100:101], v[142:143], v[98:99]
	v_pk_fma_f32 v[86:87], v[86:87], v[146:147], v[98:99]
	v_cvt_pk_f32_fp8_e32 v[98:99], v88
	v_cvt_pk_f32_fp8_sdwa v[100:101], v88 src0_sel:WORD_1
	v_pk_fma_f32 v[86:87], v[98:99], v[148:149], v[86:87]
	v_cvt_pk_f32_fp8_e32 v[98:99], v89
	v_cvt_pk_f32_fp8_sdwa v[88:89], v89 src0_sel:WORD_1
	v_pk_fma_f32 v[86:87], v[100:101], v[152:153], v[86:87]
	v_pk_fma_f32 v[86:87], v[98:99], v[150:151], v[86:87]
	v_pk_fma_f32 v[86:87], v[88:89], v[154:155], v[86:87]
	v_cvt_pk_f32_fp8_sdwa v[88:89], v78 src0_sel:WORD_1
	v_add_f32_e32 v86, v86, v87
	s_nop 1
	v_add_f32_dpp v86, v86, v86 quad_perm:[1,0,3,2] row_mask:0xf bank_mask:0xf bound_ctrl:1
	s_nop 1
	v_add_f32_dpp v86, v86, v86 quad_perm:[2,3,0,1] row_mask:0xf bank_mask:0xf bound_ctrl:1
	s_nop 1
	v_add_f32_dpp v86, v86, v86 row_half_mirror row_mask:0xf bank_mask:0xf bound_ctrl:1
	v_cndmask_b32_e64 v98, v106, v86, s[44:45]
	v_cvt_pk_f32_fp8_e32 v[86:87], v78
	v_pk_fma_f32 v[86:87], v[86:87], v[140:141], 0 op_sel_hi:[1,1,0]
	v_pk_fma_f32 v[86:87], v[88:89], v[144:145], v[86:87]
	v_cvt_pk_f32_fp8_e32 v[88:89], v79
	v_cvt_pk_f32_fp8_sdwa v[78:79], v79 src0_sel:WORD_1
	v_pk_fma_f32 v[86:87], v[88:89], v[142:143], v[86:87]
	v_pk_fma_f32 v[78:79], v[78:79], v[146:147], v[86:87]
	v_cvt_pk_f32_fp8_e32 v[86:87], v80
	v_cvt_pk_f32_fp8_sdwa v[88:89], v80 src0_sel:WORD_1
	v_pk_fma_f32 v[78:79], v[86:87], v[148:149], v[78:79]
	v_cvt_pk_f32_fp8_e32 v[86:87], v81
	v_cvt_pk_f32_fp8_sdwa v[80:81], v81 src0_sel:WORD_1
	v_pk_fma_f32 v[78:79], v[88:89], v[152:153], v[78:79]
	v_pk_fma_f32 v[78:79], v[86:87], v[150:151], v[78:79]
	v_pk_fma_f32 v[78:79], v[80:81], v[154:155], v[78:79]
	v_cvt_pk_f32_fp8_sdwa v[80:81], v70 src0_sel:WORD_1
	v_add_f32_e32 v78, v78, v79
	s_nop 1
	v_add_f32_dpp v78, v78, v78 quad_perm:[1,0,3,2] row_mask:0xf bank_mask:0xf bound_ctrl:1
	s_nop 1
	v_add_f32_dpp v78, v78, v78 quad_perm:[2,3,0,1] row_mask:0xf bank_mask:0xf bound_ctrl:1
	s_nop 1
	v_add_f32_dpp v78, v78, v78 row_half_mirror row_mask:0xf bank_mask:0xf bound_ctrl:1
	v_cndmask_b32_e64 v86, v98, v78, s[46:47]
	v_cvt_pk_f32_fp8_e32 v[78:79], v70
	v_pk_fma_f32 v[78:79], v[78:79], v[140:141], 0 op_sel_hi:[1,1,0]
	v_pk_fma_f32 v[78:79], v[80:81], v[144:145], v[78:79]
	v_cvt_pk_f32_fp8_e32 v[80:81], v71
	v_cvt_pk_f32_fp8_sdwa v[70:71], v71 src0_sel:WORD_1
	v_pk_fma_f32 v[78:79], v[80:81], v[142:143], v[78:79]
	v_pk_fma_f32 v[70:71], v[70:71], v[146:147], v[78:79]
	v_cvt_pk_f32_fp8_e32 v[78:79], v72
	v_cvt_pk_f32_fp8_sdwa v[80:81], v72 src0_sel:WORD_1
	v_pk_fma_f32 v[70:71], v[78:79], v[148:149], v[70:71]
	v_cvt_pk_f32_fp8_e32 v[78:79], v73
	v_cvt_pk_f32_fp8_sdwa v[72:73], v73 src0_sel:WORD_1
	v_pk_fma_f32 v[70:71], v[80:81], v[152:153], v[70:71]
	v_pk_fma_f32 v[70:71], v[78:79], v[150:151], v[70:71]
	v_pk_fma_f32 v[70:71], v[72:73], v[154:155], v[70:71]
	v_cvt_pk_f32_fp8_sdwa v[72:73], v58 src0_sel:WORD_1
	v_add_f32_e32 v70, v70, v71
	s_nop 1
	v_add_f32_dpp v70, v70, v70 quad_perm:[1,0,3,2] row_mask:0xf bank_mask:0xf bound_ctrl:1
	s_nop 1
	v_add_f32_dpp v70, v70, v70 quad_perm:[2,3,0,1] row_mask:0xf bank_mask:0xf bound_ctrl:1
	s_nop 1
	v_add_f32_dpp v70, v70, v70 row_half_mirror row_mask:0xf bank_mask:0xf bound_ctrl:1
	v_cndmask_b32_e64 v78, v86, v70, s[48:49]
	v_cvt_pk_f32_fp8_e32 v[70:71], v58
	v_pk_fma_f32 v[70:71], v[70:71], v[140:141], 0 op_sel_hi:[1,1,0]
	v_pk_fma_f32 v[70:71], v[72:73], v[144:145], v[70:71]
	v_cvt_pk_f32_fp8_e32 v[72:73], v59
	v_cvt_pk_f32_fp8_sdwa v[58:59], v59 src0_sel:WORD_1
	v_pk_fma_f32 v[70:71], v[72:73], v[142:143], v[70:71]
	v_pk_fma_f32 v[58:59], v[58:59], v[146:147], v[70:71]
	v_cvt_pk_f32_fp8_e32 v[70:71], v60
	v_cvt_pk_f32_fp8_sdwa v[72:73], v60 src0_sel:WORD_1
	v_pk_fma_f32 v[58:59], v[70:71], v[148:149], v[58:59]
	v_cvt_pk_f32_fp8_e32 v[70:71], v61
	v_cvt_pk_f32_fp8_sdwa v[60:61], v61 src0_sel:WORD_1
	v_pk_fma_f32 v[58:59], v[72:73], v[152:153], v[58:59]
	v_pk_fma_f32 v[58:59], v[70:71], v[150:151], v[58:59]
	v_pk_fma_f32 v[58:59], v[60:61], v[154:155], v[58:59]
	v_cvt_pk_f32_fp8_sdwa v[60:61], v50 src0_sel:WORD_1
	v_add_f32_e32 v58, v58, v59
	s_nop 1
	v_add_f32_dpp v58, v58, v58 quad_perm:[1,0,3,2] row_mask:0xf bank_mask:0xf bound_ctrl:1
	s_nop 1
	v_add_f32_dpp v58, v58, v58 quad_perm:[2,3,0,1] row_mask:0xf bank_mask:0xf bound_ctrl:1
	s_nop 1
	v_add_f32_dpp v58, v58, v58 row_half_mirror row_mask:0xf bank_mask:0xf bound_ctrl:1
	v_cndmask_b32_e64 v70, v78, v58, s[50:51]
	v_cvt_pk_f32_fp8_e32 v[58:59], v50
	v_pk_fma_f32 v[58:59], v[58:59], v[140:141], 0 op_sel_hi:[1,1,0]
	v_pk_fma_f32 v[58:59], v[60:61], v[144:145], v[58:59]
	v_cvt_pk_f32_fp8_e32 v[60:61], v51
	v_cvt_pk_f32_fp8_sdwa v[50:51], v51 src0_sel:WORD_1
	v_pk_fma_f32 v[58:59], v[60:61], v[142:143], v[58:59]
	v_pk_fma_f32 v[50:51], v[50:51], v[146:147], v[58:59]
	v_cvt_pk_f32_fp8_e32 v[58:59], v52
	v_cvt_pk_f32_fp8_sdwa v[60:61], v52 src0_sel:WORD_1
	v_pk_fma_f32 v[50:51], v[58:59], v[148:149], v[50:51]
	v_cvt_pk_f32_fp8_e32 v[58:59], v53
	v_cvt_pk_f32_fp8_sdwa v[52:53], v53 src0_sel:WORD_1
	v_pk_fma_f32 v[50:51], v[60:61], v[152:153], v[50:51]
	v_pk_fma_f32 v[50:51], v[58:59], v[150:151], v[50:51]
	v_pk_fma_f32 v[50:51], v[52:53], v[154:155], v[50:51]
	v_cvt_pk_f32_fp8_sdwa v[52:53], v42 src0_sel:WORD_1
	v_add_f32_e32 v50, v50, v51
	s_nop 1
	v_add_f32_dpp v50, v50, v50 quad_perm:[1,0,3,2] row_mask:0xf bank_mask:0xf bound_ctrl:1
	s_nop 1
	v_add_f32_dpp v50, v50, v50 quad_perm:[2,3,0,1] row_mask:0xf bank_mask:0xf bound_ctrl:1
	s_nop 1
	v_add_f32_dpp v50, v50, v50 row_half_mirror row_mask:0xf bank_mask:0xf bound_ctrl:1
	v_cndmask_b32_e64 v58, v70, v50, s[52:53]
	v_cvt_pk_f32_fp8_e32 v[50:51], v42
	v_pk_fma_f32 v[50:51], v[50:51], v[140:141], 0 op_sel_hi:[1,1,0]
	v_pk_fma_f32 v[50:51], v[52:53], v[144:145], v[50:51]
	v_cvt_pk_f32_fp8_e32 v[52:53], v43
	v_cvt_pk_f32_fp8_sdwa v[42:43], v43 src0_sel:WORD_1
	v_pk_fma_f32 v[50:51], v[52:53], v[142:143], v[50:51]
	v_pk_fma_f32 v[42:43], v[42:43], v[146:147], v[50:51]
	v_cvt_pk_f32_fp8_e32 v[50:51], v44
	v_cvt_pk_f32_fp8_sdwa v[52:53], v44 src0_sel:WORD_1
	v_pk_fma_f32 v[42:43], v[50:51], v[148:149], v[42:43]
	v_cvt_pk_f32_fp8_e32 v[50:51], v45
	v_cvt_pk_f32_fp8_sdwa v[44:45], v45 src0_sel:WORD_1
	v_pk_fma_f32 v[42:43], v[52:53], v[152:153], v[42:43]
	v_pk_fma_f32 v[42:43], v[50:51], v[150:151], v[42:43]
	v_pk_fma_f32 v[42:43], v[44:45], v[154:155], v[42:43]
	v_cvt_pk_f32_fp8_sdwa v[44:45], v34 src0_sel:WORD_1
	v_add_f32_e32 v42, v42, v43
	s_nop 1
	v_add_f32_dpp v42, v42, v42 quad_perm:[1,0,3,2] row_mask:0xf bank_mask:0xf bound_ctrl:1
	s_nop 1
	v_add_f32_dpp v42, v42, v42 quad_perm:[2,3,0,1] row_mask:0xf bank_mask:0xf bound_ctrl:1
	s_nop 1
	v_add_f32_dpp v42, v42, v42 row_half_mirror row_mask:0xf bank_mask:0xf bound_ctrl:1
	v_cndmask_b32_e64 v50, v58, v42, s[54:55]
	v_cvt_pk_f32_fp8_e32 v[42:43], v34
	v_pk_fma_f32 v[42:43], v[42:43], v[140:141], 0 op_sel_hi:[1,1,0]
	v_pk_fma_f32 v[42:43], v[44:45], v[144:145], v[42:43]
	v_cvt_pk_f32_fp8_e32 v[44:45], v35
	v_cvt_pk_f32_fp8_sdwa v[34:35], v35 src0_sel:WORD_1
	v_pk_fma_f32 v[42:43], v[44:45], v[142:143], v[42:43]
	v_pk_fma_f32 v[34:35], v[34:35], v[146:147], v[42:43]
	v_cvt_pk_f32_fp8_e32 v[42:43], v36
	v_cvt_pk_f32_fp8_sdwa v[44:45], v36 src0_sel:WORD_1
	v_pk_fma_f32 v[34:35], v[42:43], v[148:149], v[34:35]
	v_cvt_pk_f32_fp8_e32 v[42:43], v37
	v_cvt_pk_f32_fp8_sdwa v[36:37], v37 src0_sel:WORD_1
	v_pk_fma_f32 v[34:35], v[44:45], v[152:153], v[34:35]
	v_pk_fma_f32 v[34:35], v[42:43], v[150:151], v[34:35]
	v_pk_fma_f32 v[34:35], v[36:37], v[154:155], v[34:35]
	v_cvt_pk_f32_fp8_sdwa v[36:37], v26 src0_sel:WORD_1
	v_add_f32_e32 v34, v34, v35
	s_nop 1
	v_add_f32_dpp v34, v34, v34 quad_perm:[1,0,3,2] row_mask:0xf bank_mask:0xf bound_ctrl:1
	s_nop 1
	v_add_f32_dpp v34, v34, v34 quad_perm:[2,3,0,1] row_mask:0xf bank_mask:0xf bound_ctrl:1
	s_nop 1
	v_add_f32_dpp v34, v34, v34 row_half_mirror row_mask:0xf bank_mask:0xf bound_ctrl:1
	v_cndmask_b32_e32 v42, 0, v34, vcc
	v_cvt_pk_f32_fp8_e32 v[34:35], v26
	v_pk_fma_f32 v[34:35], v[34:35], v[140:141], 0 op_sel_hi:[1,1,0]
	v_pk_fma_f32 v[34:35], v[36:37], v[144:145], v[34:35]
	v_cvt_pk_f32_fp8_e32 v[36:37], v27
	v_cvt_pk_f32_fp8_sdwa v[26:27], v27 src0_sel:WORD_1
	v_pk_fma_f32 v[34:35], v[36:37], v[142:143], v[34:35]
	v_pk_fma_f32 v[26:27], v[26:27], v[146:147], v[34:35]
	v_cvt_pk_f32_fp8_e32 v[34:35], v28
	v_cvt_pk_f32_fp8_sdwa v[36:37], v28 src0_sel:WORD_1
	v_pk_fma_f32 v[26:27], v[34:35], v[148:149], v[26:27]
	v_cvt_pk_f32_fp8_e32 v[34:35], v29
	v_cvt_pk_f32_fp8_sdwa v[28:29], v29 src0_sel:WORD_1
	v_pk_fma_f32 v[26:27], v[36:37], v[152:153], v[26:27]
	v_pk_fma_f32 v[26:27], v[34:35], v[150:151], v[26:27]
	v_pk_fma_f32 v[26:27], v[28:29], v[154:155], v[26:27]
	v_cvt_pk_f32_fp8_sdwa v[28:29], v22 src0_sel:WORD_1
	v_add_f32_e32 v26, v26, v27
	s_nop 1
	v_add_f32_dpp v26, v26, v26 quad_perm:[1,0,3,2] row_mask:0xf bank_mask:0xf bound_ctrl:1
	s_nop 1
	v_add_f32_dpp v26, v26, v26 quad_perm:[2,3,0,1] row_mask:0xf bank_mask:0xf bound_ctrl:1
	s_nop 1
	v_add_f32_dpp v26, v26, v26 row_half_mirror row_mask:0xf bank_mask:0xf bound_ctrl:1
	v_cndmask_b32_e64 v34, v42, v26, s[42:43]
	v_cvt_pk_f32_fp8_e32 v[26:27], v22
	v_pk_fma_f32 v[26:27], v[26:27], v[140:141], 0 op_sel_hi:[1,1,0]
	v_pk_fma_f32 v[26:27], v[28:29], v[144:145], v[26:27]
	v_cvt_pk_f32_fp8_e32 v[28:29], v23
	v_cvt_pk_f32_fp8_sdwa v[22:23], v23 src0_sel:WORD_1
	v_pk_fma_f32 v[26:27], v[28:29], v[142:143], v[26:27]
	v_pk_fma_f32 v[22:23], v[22:23], v[146:147], v[26:27]
	v_cvt_pk_f32_fp8_e32 v[26:27], v24
	v_cvt_pk_f32_fp8_sdwa v[28:29], v24 src0_sel:WORD_1
	v_pk_fma_f32 v[22:23], v[26:27], v[148:149], v[22:23]
	v_cvt_pk_f32_fp8_e32 v[26:27], v25
	v_cvt_pk_f32_fp8_sdwa v[24:25], v25 src0_sel:WORD_1
	v_pk_fma_f32 v[22:23], v[28:29], v[152:153], v[22:23]
	v_pk_fma_f32 v[22:23], v[26:27], v[150:151], v[22:23]
	v_pk_fma_f32 v[22:23], v[24:25], v[154:155], v[22:23]
	v_cvt_pk_f32_fp8_sdwa v[24:25], v18 src0_sel:WORD_1
	v_add_f32_e32 v22, v22, v23
	s_nop 1
	v_add_f32_dpp v22, v22, v22 quad_perm:[1,0,3,2] row_mask:0xf bank_mask:0xf bound_ctrl:1
	s_nop 1
	v_add_f32_dpp v22, v22, v22 quad_perm:[2,3,0,1] row_mask:0xf bank_mask:0xf bound_ctrl:1
	s_nop 1
	v_add_f32_dpp v22, v22, v22 row_half_mirror row_mask:0xf bank_mask:0xf bound_ctrl:1
	v_cndmask_b32_e64 v26, v34, v22, s[44:45]
	v_cvt_pk_f32_fp8_e32 v[22:23], v18
	v_pk_fma_f32 v[22:23], v[22:23], v[140:141], 0 op_sel_hi:[1,1,0]
	v_pk_fma_f32 v[22:23], v[24:25], v[144:145], v[22:23]
	v_cvt_pk_f32_fp8_e32 v[24:25], v19
	v_cvt_pk_f32_fp8_sdwa v[18:19], v19 src0_sel:WORD_1
	v_pk_fma_f32 v[22:23], v[24:25], v[142:143], v[22:23]
	v_pk_fma_f32 v[18:19], v[18:19], v[146:147], v[22:23]
	v_cvt_pk_f32_fp8_e32 v[22:23], v20
	v_cvt_pk_f32_fp8_sdwa v[24:25], v20 src0_sel:WORD_1
	v_pk_fma_f32 v[18:19], v[22:23], v[148:149], v[18:19]
	v_cvt_pk_f32_fp8_e32 v[22:23], v21
	v_cvt_pk_f32_fp8_sdwa v[20:21], v21 src0_sel:WORD_1
	v_pk_fma_f32 v[18:19], v[24:25], v[152:153], v[18:19]
	v_pk_fma_f32 v[18:19], v[22:23], v[150:151], v[18:19]
	v_pk_fma_f32 v[18:19], v[20:21], v[154:155], v[18:19]
	v_cvt_pk_f32_fp8_sdwa v[20:21], v14 src0_sel:WORD_1
	v_add_f32_e32 v18, v18, v19
	s_nop 1
	v_add_f32_dpp v18, v18, v18 quad_perm:[1,0,3,2] row_mask:0xf bank_mask:0xf bound_ctrl:1
	s_nop 1
	v_add_f32_dpp v18, v18, v18 quad_perm:[2,3,0,1] row_mask:0xf bank_mask:0xf bound_ctrl:1
	s_nop 1
	v_add_f32_dpp v18, v18, v18 row_half_mirror row_mask:0xf bank_mask:0xf bound_ctrl:1
	v_cndmask_b32_e64 v22, v26, v18, s[46:47]
	v_cvt_pk_f32_fp8_e32 v[18:19], v14
	v_pk_fma_f32 v[18:19], v[18:19], v[140:141], 0 op_sel_hi:[1,1,0]
	v_pk_fma_f32 v[18:19], v[20:21], v[144:145], v[18:19]
	v_cvt_pk_f32_fp8_e32 v[20:21], v15
	v_cvt_pk_f32_fp8_sdwa v[14:15], v15 src0_sel:WORD_1
	v_pk_fma_f32 v[18:19], v[20:21], v[142:143], v[18:19]
	v_pk_fma_f32 v[14:15], v[14:15], v[146:147], v[18:19]
	v_cvt_pk_f32_fp8_e32 v[18:19], v16
	v_cvt_pk_f32_fp8_sdwa v[20:21], v16 src0_sel:WORD_1
	v_pk_fma_f32 v[14:15], v[18:19], v[148:149], v[14:15]
	v_cvt_pk_f32_fp8_e32 v[18:19], v17
	v_cvt_pk_f32_fp8_sdwa v[16:17], v17 src0_sel:WORD_1
	v_pk_fma_f32 v[14:15], v[20:21], v[152:153], v[14:15]
	v_pk_fma_f32 v[14:15], v[18:19], v[150:151], v[14:15]
	v_pk_fma_f32 v[14:15], v[16:17], v[154:155], v[14:15]
	v_cvt_pk_f32_fp8_sdwa v[16:17], v10 src0_sel:WORD_1
	v_add_f32_e32 v14, v14, v15
	s_nop 1
	v_add_f32_dpp v14, v14, v14 quad_perm:[1,0,3,2] row_mask:0xf bank_mask:0xf bound_ctrl:1
	s_nop 1
	v_add_f32_dpp v14, v14, v14 quad_perm:[2,3,0,1] row_mask:0xf bank_mask:0xf bound_ctrl:1
	s_nop 1
	v_add_f32_dpp v14, v14, v14 row_half_mirror row_mask:0xf bank_mask:0xf bound_ctrl:1
	v_cndmask_b32_e64 v18, v22, v14, s[48:49]
	v_cvt_pk_f32_fp8_e32 v[14:15], v10
	v_pk_fma_f32 v[14:15], v[14:15], v[140:141], 0 op_sel_hi:[1,1,0]
	v_pk_fma_f32 v[14:15], v[16:17], v[144:145], v[14:15]
	v_cvt_pk_f32_fp8_e32 v[16:17], v11
	v_cvt_pk_f32_fp8_sdwa v[10:11], v11 src0_sel:WORD_1
	v_pk_fma_f32 v[14:15], v[16:17], v[142:143], v[14:15]
	v_pk_fma_f32 v[10:11], v[10:11], v[146:147], v[14:15]
	v_cvt_pk_f32_fp8_e32 v[14:15], v12
	v_cvt_pk_f32_fp8_sdwa v[16:17], v12 src0_sel:WORD_1
	v_pk_fma_f32 v[10:11], v[14:15], v[148:149], v[10:11]
	v_cvt_pk_f32_fp8_e32 v[14:15], v13
	v_cvt_pk_f32_fp8_sdwa v[12:13], v13 src0_sel:WORD_1
	v_pk_fma_f32 v[10:11], v[16:17], v[152:153], v[10:11]
	v_pk_fma_f32 v[10:11], v[14:15], v[150:151], v[10:11]
	v_pk_fma_f32 v[10:11], v[12:13], v[154:155], v[10:11]
	v_cvt_pk_f32_fp8_sdwa v[12:13], v6 src0_sel:WORD_1
	v_add_f32_e32 v10, v10, v11
	s_nop 1
	v_add_f32_dpp v10, v10, v10 quad_perm:[1,0,3,2] row_mask:0xf bank_mask:0xf bound_ctrl:1
	s_nop 1
	v_add_f32_dpp v10, v10, v10 quad_perm:[2,3,0,1] row_mask:0xf bank_mask:0xf bound_ctrl:1
	s_nop 1
	v_add_f32_dpp v10, v10, v10 row_half_mirror row_mask:0xf bank_mask:0xf bound_ctrl:1
	v_cndmask_b32_e64 v14, v18, v10, s[50:51]
	v_cvt_pk_f32_fp8_e32 v[10:11], v6
	v_pk_fma_f32 v[10:11], v[10:11], v[140:141], 0 op_sel_hi:[1,1,0]
	v_pk_fma_f32 v[10:11], v[12:13], v[144:145], v[10:11]
	v_cvt_pk_f32_fp8_e32 v[12:13], v7
	v_cvt_pk_f32_fp8_sdwa v[6:7], v7 src0_sel:WORD_1
	v_pk_fma_f32 v[10:11], v[12:13], v[142:143], v[10:11]
	v_pk_fma_f32 v[6:7], v[6:7], v[146:147], v[10:11]
	v_cvt_pk_f32_fp8_e32 v[10:11], v8
	v_cvt_pk_f32_fp8_sdwa v[12:13], v8 src0_sel:WORD_1
	v_pk_fma_f32 v[6:7], v[10:11], v[148:149], v[6:7]
	v_cvt_pk_f32_fp8_e32 v[10:11], v9
	v_cvt_pk_f32_fp8_sdwa v[8:9], v9 src0_sel:WORD_1
	v_pk_fma_f32 v[6:7], v[12:13], v[152:153], v[6:7]
	v_pk_fma_f32 v[6:7], v[10:11], v[150:151], v[6:7]
	v_pk_fma_f32 v[6:7], v[8:9], v[154:155], v[6:7]
	v_cvt_pk_f32_fp8_sdwa v[8:9], v2 src0_sel:WORD_1
	v_add_f32_e32 v6, v6, v7
	s_nop 1
	v_add_f32_dpp v6, v6, v6 quad_perm:[1,0,3,2] row_mask:0xf bank_mask:0xf bound_ctrl:1
	s_nop 1
	v_add_f32_dpp v6, v6, v6 quad_perm:[2,3,0,1] row_mask:0xf bank_mask:0xf bound_ctrl:1
	s_nop 1
	v_add_f32_dpp v6, v6, v6 row_half_mirror row_mask:0xf bank_mask:0xf bound_ctrl:1
	v_cndmask_b32_e64 v10, v14, v6, s[52:53]
	v_cvt_pk_f32_fp8_e32 v[6:7], v2
	v_pk_fma_f32 v[6:7], v[6:7], v[140:141], 0 op_sel_hi:[1,1,0]
	v_pk_fma_f32 v[6:7], v[8:9], v[144:145], v[6:7]
	v_cvt_pk_f32_fp8_e32 v[8:9], v3
	v_cvt_pk_f32_fp8_sdwa v[2:3], v3 src0_sel:WORD_1
	s_waitcnt vmcnt(2)
	ds_bpermute_b32 v140, v164, v0
	ds_bpermute_b32 v145, v167, v175
	v_pk_fma_f32 v[6:7], v[8:9], v[142:143], v[6:7]
	v_cvt_pk_f32_fp8_sdwa v[8:9], v4 src0_sel:WORD_1
	v_pk_fma_f32 v[2:3], v[2:3], v[146:147], v[6:7]
	v_cvt_pk_f32_fp8_e32 v[6:7], v4
	ds_bpermute_b32 v147, v168, v175
	s_waitcnt lgkmcnt(1)
	v_lshlrev_b32_e32 v144, 16, v145
	v_and_b32_e32 v145, 0xffff0000, v145
	v_pk_fma_f32 v[2:3], v[6:7], v[148:149], v[2:3]
	v_cvt_pk_f32_fp8_e32 v[6:7], v5
	v_cvt_pk_f32_fp8_sdwa v[4:5], v5 src0_sel:WORD_1
	v_pk_fma_f32 v[2:3], v[8:9], v[152:153], v[2:3]
	ds_bpermute_b32 v8, v161, v0
	v_pk_fma_f32 v[2:3], v[6:7], v[150:151], v[2:3]
	ds_bpermute_b32 v6, v159, v0
	v_pk_fma_f32 v[2:3], v[4:5], v[154:155], v[2:3]
	ds_bpermute_b32 v4, v156, v0
	v_add_f32_e32 v2, v2, v3
	ds_bpermute_b32 v5, v158, v0
	ds_bpermute_b32 v7, v160, v0
	v_add_f32_dpp v2, v2, v2 quad_perm:[1,0,3,2] row_mask:0xf bank_mask:0xf bound_ctrl:1
	ds_bpermute_b32 v9, v162, v0
	v_cvt_pk_bf16_f32 v3, v50, s0
	v_add_f32_dpp v2, v2, v2 quad_perm:[2,3,0,1] row_mask:0xf bank_mask:0xf bound_ctrl:1
	global_store_short v[138:139], v3, off offset:-16
	ds_bpermute_b32 v149, v169, v175
	v_add_f32_dpp v2, v2, v2 row_half_mirror row_mask:0xf bank_mask:0xf bound_ctrl:1
	v_cndmask_b32_e64 v2, v10, v2, s[54:55]
	ds_bpermute_b32 v10, v163, v0
	s_waitcnt lgkmcnt(5)
	v_lshlrev_b32_e32 v0, 7, v4
	v_cvt_pk_bf16_f32 v2, v2, s0
	v_and_b32_e32 v0, 0x7fff80, v0
	global_store_short v[138:139], v2, off
	v_lshl_add_u64 v[2:3], v[134:135], 0, v[0:1]
	v_lshlrev_b32_sdwa v0, v231, v4 dst_sel:DWORD dst_unused:UNUSED_PAD src0_sel:DWORD src1_sel:WORD_1
	global_load_dwordx4 v[106:109], v[2:3], off
	v_lshl_add_u64 v[2:3], v[134:135], 0, v[0:1]
	s_waitcnt lgkmcnt(4)
	v_lshlrev_b32_e32 v0, 7, v5
	v_and_b32_e32 v0, 0x7fff80, v0
	global_load_dwordx4 v[98:101], v[2:3], off
	v_lshl_add_u64 v[2:3], v[134:135], 0, v[0:1]
	v_lshlrev_b32_sdwa v0, v231, v5 dst_sel:DWORD dst_unused:UNUSED_PAD src0_sel:DWORD src1_sel:WORD_1
	global_load_dwordx4 v[86:89], v[2:3], off
	v_lshl_add_u64 v[2:3], v[134:135], 0, v[0:1]
	v_lshlrev_b32_e32 v0, 7, v6
	v_and_b32_e32 v0, 0x7fff80, v0
	global_load_dwordx4 v[78:81], v[2:3], off
	v_lshl_add_u64 v[2:3], v[134:135], 0, v[0:1]
	v_lshlrev_b32_sdwa v0, v231, v6 dst_sel:DWORD dst_unused:UNUSED_PAD src0_sel:DWORD src1_sel:WORD_1
	global_load_dwordx4 v[70:73], v[2:3], off
	v_lshl_add_u64 v[2:3], v[134:135], 0, v[0:1]
	s_waitcnt lgkmcnt(3)
	v_lshlrev_b32_e32 v0, 7, v7
	v_and_b32_e32 v0, 0x7fff80, v0
	global_load_dwordx4 v[58:61], v[2:3], off
	v_lshl_add_u64 v[2:3], v[134:135], 0, v[0:1]
	v_lshlrev_b32_sdwa v0, v231, v7 dst_sel:DWORD dst_unused:UNUSED_PAD src0_sel:DWORD src1_sel:WORD_1
	global_load_dwordx4 v[50:53], v[2:3], off
	v_lshl_add_u64 v[2:3], v[134:135], 0, v[0:1]
	v_lshlrev_b32_e32 v0, 7, v8
	v_and_b32_e32 v0, 0x7fff80, v0
	global_load_dwordx4 v[42:45], v[2:3], off
	v_lshl_add_u64 v[2:3], v[134:135], 0, v[0:1]
	v_lshlrev_b32_sdwa v0, v231, v8 dst_sel:DWORD dst_unused:UNUSED_PAD src0_sel:DWORD src1_sel:WORD_1
	global_load_dwordx4 v[34:37], v[2:3], off
	v_lshl_add_u64 v[2:3], v[134:135], 0, v[0:1]
	s_waitcnt lgkmcnt(2)
	v_lshlrev_b32_e32 v0, 7, v9
	v_and_b32_e32 v0, 0x7fff80, v0
	global_load_dwordx4 v[26:29], v[2:3], off
	v_lshl_add_u64 v[2:3], v[134:135], 0, v[0:1]
	v_lshlrev_b32_sdwa v0, v231, v9 dst_sel:DWORD dst_unused:UNUSED_PAD src0_sel:DWORD src1_sel:WORD_1
	global_load_dwordx4 v[22:25], v[2:3], off
	v_lshl_add_u64 v[2:3], v[134:135], 0, v[0:1]
	s_waitcnt lgkmcnt(0)
	v_lshlrev_b32_e32 v0, 7, v10
	v_and_b32_e32 v0, 0x7fff80, v0
	global_load_dwordx4 v[18:21], v[2:3], off
	v_lshl_add_u64 v[2:3], v[134:135], 0, v[0:1]
	v_lshlrev_b32_sdwa v0, v231, v10 dst_sel:DWORD dst_unused:UNUSED_PAD src0_sel:DWORD src1_sel:WORD_1
	global_load_dwordx4 v[14:17], v[2:3], off
	v_lshl_add_u64 v[2:3], v[134:135], 0, v[0:1]
	v_lshlrev_b32_e32 v0, 7, v140
	v_and_b32_e32 v0, 0x7fff80, v0
	global_load_dwordx4 v[10:13], v[2:3], off
	v_lshl_add_u64 v[2:3], v[134:135], 0, v[0:1]
	v_lshlrev_b32_sdwa v0, v231, v140 dst_sel:DWORD dst_unused:UNUSED_PAD src0_sel:DWORD src1_sel:WORD_1
	v_readlane_b32 s0, v254, 51
	global_load_dwordx4 v[6:9], v[2:3], off
	v_lshl_add_u64 v[2:3], v[134:135], 0, v[0:1]
	v_add_u32_e32 v0, s0, v174
	v_min_i32_e32 v140, 0x13fff, v0
	v_ashrrev_i32_e32 v141, 31, v140
	v_lshlrev_b64 v[142:143], 11, v[140:141]
	v_lshlrev_b64 v[140:141], 8, v[140:141]
	v_lshl_add_u64 v[140:141], v[132:133], 0, v[140:141]
	v_lshl_add_u64 v[142:143], v[130:131], 0, v[142:143]
	global_load_dword v176, v[140:141], off
	ds_bpermute_b32 v141, v165, v175
	global_load_dword v0, v[142:143], off
	ds_bpermute_b32 v143, v166, v175
	v_lshlrev_b32_e32 v146, 16, v147
	v_and_b32_e32 v147, 0xffff0000, v147
	s_waitcnt lgkmcnt(1)
	v_lshlrev_b32_e32 v140, 16, v141
	v_and_b32_e32 v141, 0xffff0000, v141
	s_waitcnt lgkmcnt(0)
	v_lshlrev_b32_e32 v142, 16, v143
	v_and_b32_e32 v143, 0xffff0000, v143
	v_pk_fma_f32 v[178:179], v[178:179], v[140:141], 0 op_sel_hi:[1,1,0]
	ds_bpermute_b32 v150, v170, v175
	v_pk_fma_f32 v[178:179], v[180:181], v[142:143], v[178:179]
	v_cvt_pk_f32_fp8_e32 v[180:181], v127
	v_cvt_pk_f32_fp8_sdwa v[126:127], v127 src0_sel:WORD_1
	ds_bpermute_b32 v151, v171, v175
	v_lshlrev_b32_e32 v148, 16, v149
	v_pk_fma_f32 v[178:179], v[180:181], v[144:145], v[178:179]
	v_and_b32_e32 v149, 0xffff0000, v149
	v_pk_fma_f32 v[126:127], v[126:127], v[146:147], v[178:179]
	v_cvt_pk_f32_fp8_e32 v[178:179], v128
	ds_bpermute_b32 v155, v172, v175
	v_cvt_pk_f32_fp8_sdwa v[180:181], v128 src0_sel:WORD_1
	s_waitcnt lgkmcnt(2)
	v_lshlrev_b32_e32 v152, 16, v150
	v_pk_fma_f32 v[126:127], v[178:179], v[148:149], v[126:127]
	v_cvt_pk_f32_fp8_e32 v[178:179], v129
	v_cvt_pk_f32_fp8_sdwa v[128:129], v129 src0_sel:WORD_1
	v_and_b32_e32 v153, 0xffff0000, v150
	s_waitcnt lgkmcnt(1)
	v_lshlrev_b32_e32 v150, 16, v151
	v_and_b32_e32 v151, 0xffff0000, v151
	v_pk_fma_f32 v[126:127], v[180:181], v[152:153], v[126:127]
	s_waitcnt lgkmcnt(0)
	v_lshlrev_b32_e32 v154, 16, v155
	v_and_b32_e32 v155, 0xffff0000, v155
	v_pk_fma_f32 v[126:127], v[178:179], v[150:151], v[126:127]
	v_cvt_pk_f32_fp8_sdwa v[178:179], v122 src0_sel:WORD_1
	v_pk_fma_f32 v[126:127], v[128:129], v[154:155], v[126:127]
	v_cvt_pk_f32_fp8_e32 v[128:129], v122
	global_load_dwordx4 v[2:5], v[2:3], off
	v_add_f32_e32 v126, v126, v127
	v_pk_fma_f32 v[128:129], v[128:129], v[140:141], 0 op_sel_hi:[1,1,0]
	v_pk_fma_f32 v[128:129], v[178:179], v[142:143], v[128:129]
	v_cvt_pk_f32_fp8_e32 v[178:179], v123
	v_cvt_pk_f32_fp8_sdwa v[122:123], v123 src0_sel:WORD_1
	v_add_f32_dpp v126, v126, v126 quad_perm:[1,0,3,2] row_mask:0xf bank_mask:0xf bound_ctrl:1
	v_pk_fma_f32 v[128:129], v[178:179], v[144:145], v[128:129]
	v_pk_fma_f32 v[122:123], v[122:123], v[146:147], v[128:129]
	v_cvt_pk_f32_fp8_e32 v[128:129], v124
	v_cvt_pk_f32_fp8_sdwa v[178:179], v124 src0_sel:WORD_1
	v_add_f32_dpp v126, v126, v126 quad_perm:[2,3,0,1] row_mask:0xf bank_mask:0xf bound_ctrl:1
	v_pk_fma_f32 v[122:123], v[128:129], v[148:149], v[122:123]
	v_cvt_pk_f32_fp8_e32 v[128:129], v125
	v_cvt_pk_f32_fp8_sdwa v[124:125], v125 src0_sel:WORD_1
	v_pk_fma_f32 v[122:123], v[178:179], v[152:153], v[122:123]
	v_mov_b32_dpp v127, v126 row_half_mirror row_mask:0xf bank_mask:0xf bound_ctrl:1
	v_pk_fma_f32 v[122:123], v[128:129], v[150:151], v[122:123]
	v_cvt_pk_f32_fp8_sdwa v[128:129], v118 src0_sel:WORD_1
	v_pk_fma_f32 v[122:123], v[124:125], v[154:155], v[122:123]
	v_cvt_pk_f32_fp8_e32 v[124:125], v118
	v_add_f32_e32 v122, v122, v123
	v_pk_fma_f32 v[124:125], v[124:125], v[140:141], 0 op_sel_hi:[1,1,0]
	v_pk_fma_f32 v[124:125], v[128:129], v[142:143], v[124:125]
	v_cvt_pk_f32_fp8_e32 v[128:129], v119
	v_cvt_pk_f32_fp8_sdwa v[118:119], v119 src0_sel:WORD_1
	v_add_f32_dpp v122, v122, v122 quad_perm:[1,0,3,2] row_mask:0xf bank_mask:0xf bound_ctrl:1
	v_pk_fma_f32 v[124:125], v[128:129], v[144:145], v[124:125]
	v_pk_fma_f32 v[118:119], v[118:119], v[146:147], v[124:125]
	v_cvt_pk_f32_fp8_e32 v[124:125], v120
	v_cvt_pk_f32_fp8_sdwa v[128:129], v120 src0_sel:WORD_1
	v_add_f32_dpp v122, v122, v122 quad_perm:[2,3,0,1] row_mask:0xf bank_mask:0xf bound_ctrl:1
	v_pk_fma_f32 v[118:119], v[124:125], v[148:149], v[118:119]
	v_cvt_pk_f32_fp8_e32 v[124:125], v121
	v_cvt_pk_f32_fp8_sdwa v[120:121], v121 src0_sel:WORD_1
	v_pk_fma_f32 v[118:119], v[128:129], v[152:153], v[118:119]
	v_mov_b32_dpp v123, v122 row_half_mirror row_mask:0xf bank_mask:0xf bound_ctrl:1
	v_pk_fma_f32 v[118:119], v[124:125], v[150:151], v[118:119]
	v_cvt_pk_f32_fp8_sdwa v[124:125], v114 src0_sel:WORD_1
	v_pk_fma_f32 v[118:119], v[120:121], v[154:155], v[118:119]
	v_cvt_pk_f32_fp8_e32 v[120:121], v114
	v_add_f32_e32 v118, v118, v119
	v_pk_fma_f32 v[120:121], v[120:121], v[140:141], 0 op_sel_hi:[1,1,0]
	v_pk_fma_f32 v[120:121], v[124:125], v[142:143], v[120:121]
	v_cvt_pk_f32_fp8_e32 v[124:125], v115
	v_cvt_pk_f32_fp8_sdwa v[114:115], v115 src0_sel:WORD_1
	v_add_f32_dpp v118, v118, v118 quad_perm:[1,0,3,2] row_mask:0xf bank_mask:0xf bound_ctrl:1
	v_pk_fma_f32 v[120:121], v[124:125], v[144:145], v[120:121]
	v_pk_fma_f32 v[114:115], v[114:115], v[146:147], v[120:121]
	v_cvt_pk_f32_fp8_e32 v[120:121], v116
	v_cvt_pk_f32_fp8_sdwa v[124:125], v116 src0_sel:WORD_1
	v_add_f32_dpp v118, v118, v118 quad_perm:[2,3,0,1] row_mask:0xf bank_mask:0xf bound_ctrl:1
	v_pk_fma_f32 v[114:115], v[120:121], v[148:149], v[114:115]
	v_cvt_pk_f32_fp8_e32 v[120:121], v117
	v_cvt_pk_f32_fp8_sdwa v[116:117], v117 src0_sel:WORD_1
	v_pk_fma_f32 v[114:115], v[124:125], v[152:153], v[114:115]
	v_mov_b32_dpp v119, v118 row_half_mirror row_mask:0xf bank_mask:0xf bound_ctrl:1
	v_pk_fma_f32 v[114:115], v[120:121], v[150:151], v[114:115]
	v_cvt_pk_f32_fp8_sdwa v[120:121], v110 src0_sel:WORD_1
	v_pk_fma_f32 v[114:115], v[116:117], v[154:155], v[114:115]
	v_cvt_pk_f32_fp8_e32 v[116:117], v110
	v_add_f32_e32 v114, v114, v115
	v_pk_fma_f32 v[116:117], v[116:117], v[140:141], 0 op_sel_hi:[1,1,0]
	v_pk_fma_f32 v[116:117], v[120:121], v[142:143], v[116:117]
	v_cvt_pk_f32_fp8_e32 v[120:121], v111
	v_cvt_pk_f32_fp8_sdwa v[110:111], v111 src0_sel:WORD_1
	v_add_f32_dpp v114, v114, v114 quad_perm:[1,0,3,2] row_mask:0xf bank_mask:0xf bound_ctrl:1
	v_pk_fma_f32 v[116:117], v[120:121], v[144:145], v[116:117]
	v_pk_fma_f32 v[110:111], v[110:111], v[146:147], v[116:117]
	v_cvt_pk_f32_fp8_e32 v[116:117], v112
	v_cvt_pk_f32_fp8_sdwa v[120:121], v112 src0_sel:WORD_1
	v_add_f32_dpp v114, v114, v114 quad_perm:[2,3,0,1] row_mask:0xf bank_mask:0xf bound_ctrl:1
	v_pk_fma_f32 v[110:111], v[116:117], v[148:149], v[110:111]
	v_cvt_pk_f32_fp8_e32 v[116:117], v113
	v_cvt_pk_f32_fp8_sdwa v[112:113], v113 src0_sel:WORD_1
	v_pk_fma_f32 v[110:111], v[120:121], v[152:153], v[110:111]
	v_mov_b32_dpp v115, v114 row_half_mirror row_mask:0xf bank_mask:0xf bound_ctrl:1
	v_pk_fma_f32 v[110:111], v[116:117], v[150:151], v[110:111]
	v_cvt_pk_f32_fp8_sdwa v[116:117], v102 src0_sel:WORD_1
	v_pk_fma_f32 v[110:111], v[112:113], v[154:155], v[110:111]
	v_cvt_pk_f32_fp8_e32 v[112:113], v102
	v_add_f32_e32 v110, v110, v111
	v_pk_fma_f32 v[112:113], v[112:113], v[140:141], 0 op_sel_hi:[1,1,0]
	v_pk_fma_f32 v[112:113], v[116:117], v[142:143], v[112:113]
	v_cvt_pk_f32_fp8_e32 v[116:117], v103
	v_cvt_pk_f32_fp8_sdwa v[102:103], v103 src0_sel:WORD_1
	v_add_f32_dpp v110, v110, v110 quad_perm:[1,0,3,2] row_mask:0xf bank_mask:0xf bound_ctrl:1
	v_pk_fma_f32 v[112:113], v[116:117], v[144:145], v[112:113]
	v_pk_fma_f32 v[102:103], v[102:103], v[146:147], v[112:113]
	v_cvt_pk_f32_fp8_e32 v[112:113], v104
	v_cvt_pk_f32_fp8_sdwa v[116:117], v104 src0_sel:WORD_1
	v_add_f32_dpp v110, v110, v110 quad_perm:[2,3,0,1] row_mask:0xf bank_mask:0xf bound_ctrl:1
	v_pk_fma_f32 v[102:103], v[112:113], v[148:149], v[102:103]
	v_cvt_pk_f32_fp8_e32 v[112:113], v105
	v_cvt_pk_f32_fp8_sdwa v[104:105], v105 src0_sel:WORD_1
	v_pk_fma_f32 v[102:103], v[116:117], v[152:153], v[102:103]
	v_mov_b32_dpp v111, v110 row_half_mirror row_mask:0xf bank_mask:0xf bound_ctrl:1
	v_pk_fma_f32 v[102:103], v[112:113], v[150:151], v[102:103]
	v_cvt_pk_f32_fp8_sdwa v[112:113], v94 src0_sel:WORD_1
	v_pk_fma_f32 v[102:103], v[104:105], v[154:155], v[102:103]
	v_cvt_pk_f32_fp8_e32 v[104:105], v94
	v_add_f32_e32 v102, v102, v103
	v_pk_fma_f32 v[104:105], v[104:105], v[140:141], 0 op_sel_hi:[1,1,0]
	v_pk_fma_f32 v[104:105], v[112:113], v[142:143], v[104:105]
	v_cvt_pk_f32_fp8_e32 v[112:113], v95
	v_cvt_pk_f32_fp8_sdwa v[94:95], v95 src0_sel:WORD_1
	v_add_f32_dpp v102, v102, v102 quad_perm:[1,0,3,2] row_mask:0xf bank_mask:0xf bound_ctrl:1
	v_pk_fma_f32 v[104:105], v[112:113], v[144:145], v[104:105]
	v_pk_fma_f32 v[94:95], v[94:95], v[146:147], v[104:105]
	v_cvt_pk_f32_fp8_e32 v[104:105], v96
	v_cvt_pk_f32_fp8_sdwa v[112:113], v96 src0_sel:WORD_1
	v_add_f32_dpp v102, v102, v102 quad_perm:[2,3,0,1] row_mask:0xf bank_mask:0xf bound_ctrl:1
	v_pk_fma_f32 v[94:95], v[104:105], v[148:149], v[94:95]
	v_cvt_pk_f32_fp8_e32 v[104:105], v97
	v_cvt_pk_f32_fp8_sdwa v[96:97], v97 src0_sel:WORD_1
	v_pk_fma_f32 v[94:95], v[112:113], v[152:153], v[94:95]
	v_mov_b32_dpp v103, v102 row_half_mirror row_mask:0xf bank_mask:0xf bound_ctrl:1
	v_pk_fma_f32 v[94:95], v[104:105], v[150:151], v[94:95]
	v_cvt_pk_f32_fp8_sdwa v[104:105], v90 src0_sel:WORD_1
	v_pk_fma_f32 v[94:95], v[96:97], v[154:155], v[94:95]
	v_cvt_pk_f32_fp8_e32 v[96:97], v90
	v_add_f32_e32 v94, v94, v95
	v_pk_fma_f32 v[96:97], v[96:97], v[140:141], 0 op_sel_hi:[1,1,0]
	v_pk_fma_f32 v[96:97], v[104:105], v[142:143], v[96:97]
	v_cvt_pk_f32_fp8_e32 v[104:105], v91
	v_cvt_pk_f32_fp8_sdwa v[90:91], v91 src0_sel:WORD_1
	v_add_f32_dpp v94, v94, v94 quad_perm:[1,0,3,2] row_mask:0xf bank_mask:0xf bound_ctrl:1
	v_pk_fma_f32 v[96:97], v[104:105], v[144:145], v[96:97]
	v_pk_fma_f32 v[90:91], v[90:91], v[146:147], v[96:97]
	v_cvt_pk_f32_fp8_e32 v[96:97], v92
	v_cvt_pk_f32_fp8_sdwa v[104:105], v92 src0_sel:WORD_1
	v_add_f32_dpp v94, v94, v94 quad_perm:[2,3,0,1] row_mask:0xf bank_mask:0xf bound_ctrl:1
	v_pk_fma_f32 v[90:91], v[96:97], v[148:149], v[90:91]
	v_cvt_pk_f32_fp8_e32 v[96:97], v93
	v_cvt_pk_f32_fp8_sdwa v[92:93], v93 src0_sel:WORD_1
	v_pk_fma_f32 v[90:91], v[104:105], v[152:153], v[90:91]
	v_mov_b32_dpp v95, v94 row_half_mirror row_mask:0xf bank_mask:0xf bound_ctrl:1
	v_pk_fma_f32 v[90:91], v[96:97], v[150:151], v[90:91]
	v_cvt_pk_f32_fp8_sdwa v[96:97], v82 src0_sel:WORD_1
	v_pk_fma_f32 v[90:91], v[92:93], v[154:155], v[90:91]
	v_cvt_pk_f32_fp8_e32 v[92:93], v82
	v_add_f32_e32 v90, v90, v91
	v_pk_fma_f32 v[92:93], v[92:93], v[140:141], 0 op_sel_hi:[1,1,0]
	v_pk_fma_f32 v[92:93], v[96:97], v[142:143], v[92:93]
	v_cvt_pk_f32_fp8_e32 v[96:97], v83
	v_cvt_pk_f32_fp8_sdwa v[82:83], v83 src0_sel:WORD_1
	v_add_f32_dpp v90, v90, v90 quad_perm:[1,0,3,2] row_mask:0xf bank_mask:0xf bound_ctrl:1
	v_pk_fma_f32 v[92:93], v[96:97], v[144:145], v[92:93]
	v_pk_fma_f32 v[82:83], v[82:83], v[146:147], v[92:93]
	v_cvt_pk_f32_fp8_e32 v[92:93], v84
	v_cvt_pk_f32_fp8_sdwa v[96:97], v84 src0_sel:WORD_1
	v_add_f32_dpp v90, v90, v90 quad_perm:[2,3,0,1] row_mask:0xf bank_mask:0xf bound_ctrl:1
	v_pk_fma_f32 v[82:83], v[92:93], v[148:149], v[82:83]
	v_cvt_pk_f32_fp8_e32 v[92:93], v85
	v_cvt_pk_f32_fp8_sdwa v[84:85], v85 src0_sel:WORD_1
	v_pk_fma_f32 v[82:83], v[96:97], v[152:153], v[82:83]
	v_mov_b32_dpp v91, v90 row_half_mirror row_mask:0xf bank_mask:0xf bound_ctrl:1
	v_pk_fma_f32 v[82:83], v[92:93], v[150:151], v[82:83]
	v_cvt_pk_f32_fp8_sdwa v[92:93], v74 src0_sel:WORD_1
	v_pk_fma_f32 v[82:83], v[84:85], v[154:155], v[82:83]
	v_cvt_pk_f32_fp8_e32 v[84:85], v74
	v_add_f32_e32 v82, v82, v83
	v_pk_fma_f32 v[84:85], v[84:85], v[140:141], 0 op_sel_hi:[1,1,0]
	v_pk_fma_f32 v[84:85], v[92:93], v[142:143], v[84:85]
	v_cvt_pk_f32_fp8_e32 v[92:93], v75
	v_cvt_pk_f32_fp8_sdwa v[74:75], v75 src0_sel:WORD_1
	v_add_f32_dpp v82, v82, v82 quad_perm:[1,0,3,2] row_mask:0xf bank_mask:0xf bound_ctrl:1
	v_pk_fma_f32 v[84:85], v[92:93], v[144:145], v[84:85]
	v_pk_fma_f32 v[74:75], v[74:75], v[146:147], v[84:85]
	v_cvt_pk_f32_fp8_e32 v[84:85], v76
	v_cvt_pk_f32_fp8_sdwa v[92:93], v76 src0_sel:WORD_1
	v_add_f32_dpp v82, v82, v82 quad_perm:[2,3,0,1] row_mask:0xf bank_mask:0xf bound_ctrl:1
	v_pk_fma_f32 v[74:75], v[84:85], v[148:149], v[74:75]
	v_cvt_pk_f32_fp8_e32 v[84:85], v77
	v_cvt_pk_f32_fp8_sdwa v[76:77], v77 src0_sel:WORD_1
	v_pk_fma_f32 v[74:75], v[92:93], v[152:153], v[74:75]
	v_mov_b32_dpp v83, v82 row_half_mirror row_mask:0xf bank_mask:0xf bound_ctrl:1
	v_pk_fma_f32 v[74:75], v[84:85], v[150:151], v[74:75]
	v_cvt_pk_f32_fp8_sdwa v[84:85], v66 src0_sel:WORD_1
	v_pk_fma_f32 v[74:75], v[76:77], v[154:155], v[74:75]
	v_cvt_pk_f32_fp8_e32 v[76:77], v66
	v_add_f32_e32 v74, v74, v75
	v_pk_fma_f32 v[76:77], v[76:77], v[140:141], 0 op_sel_hi:[1,1,0]
	v_pk_fma_f32 v[76:77], v[84:85], v[142:143], v[76:77]
	v_cvt_pk_f32_fp8_e32 v[84:85], v67
	v_cvt_pk_f32_fp8_sdwa v[66:67], v67 src0_sel:WORD_1
	v_add_f32_dpp v74, v74, v74 quad_perm:[1,0,3,2] row_mask:0xf bank_mask:0xf bound_ctrl:1
	v_pk_fma_f32 v[76:77], v[84:85], v[144:145], v[76:77]
	v_pk_fma_f32 v[66:67], v[66:67], v[146:147], v[76:77]
	v_cvt_pk_f32_fp8_e32 v[76:77], v68
	v_cvt_pk_f32_fp8_sdwa v[84:85], v68 src0_sel:WORD_1
	v_add_f32_dpp v74, v74, v74 quad_perm:[2,3,0,1] row_mask:0xf bank_mask:0xf bound_ctrl:1
	v_pk_fma_f32 v[66:67], v[76:77], v[148:149], v[66:67]
	v_cvt_pk_f32_fp8_e32 v[76:77], v69
	v_cvt_pk_f32_fp8_sdwa v[68:69], v69 src0_sel:WORD_1
	v_pk_fma_f32 v[66:67], v[84:85], v[152:153], v[66:67]
	v_mov_b32_dpp v75, v74 row_half_mirror row_mask:0xf bank_mask:0xf bound_ctrl:1
	v_pk_fma_f32 v[66:67], v[76:77], v[150:151], v[66:67]
	v_cvt_pk_f32_fp8_sdwa v[76:77], v62 src0_sel:WORD_1
	v_pk_fma_f32 v[66:67], v[68:69], v[154:155], v[66:67]
	v_cvt_pk_f32_fp8_e32 v[68:69], v62
	v_add_f32_e32 v66, v66, v67
	v_pk_fma_f32 v[68:69], v[68:69], v[140:141], 0 op_sel_hi:[1,1,0]
	v_pk_fma_f32 v[68:69], v[76:77], v[142:143], v[68:69]
	v_cvt_pk_f32_fp8_e32 v[76:77], v63
	v_cvt_pk_f32_fp8_sdwa v[62:63], v63 src0_sel:WORD_1
	v_add_f32_dpp v66, v66, v66 quad_perm:[1,0,3,2] row_mask:0xf bank_mask:0xf bound_ctrl:1
	v_pk_fma_f32 v[68:69], v[76:77], v[144:145], v[68:69]
	v_pk_fma_f32 v[62:63], v[62:63], v[146:147], v[68:69]
	v_cvt_pk_f32_fp8_e32 v[68:69], v64
	v_cvt_pk_f32_fp8_sdwa v[76:77], v64 src0_sel:WORD_1
	v_add_f32_dpp v66, v66, v66 quad_perm:[2,3,0,1] row_mask:0xf bank_mask:0xf bound_ctrl:1
	v_pk_fma_f32 v[62:63], v[68:69], v[148:149], v[62:63]
	v_cvt_pk_f32_fp8_e32 v[68:69], v65
	v_cvt_pk_f32_fp8_sdwa v[64:65], v65 src0_sel:WORD_1
	v_pk_fma_f32 v[62:63], v[76:77], v[152:153], v[62:63]
	v_mov_b32_dpp v67, v66 row_half_mirror row_mask:0xf bank_mask:0xf bound_ctrl:1
	v_pk_fma_f32 v[62:63], v[68:69], v[150:151], v[62:63]
	v_cvt_pk_f32_fp8_sdwa v[68:69], v54 src0_sel:WORD_1
	v_pk_fma_f32 v[62:63], v[64:65], v[154:155], v[62:63]
	v_cvt_pk_f32_fp8_e32 v[64:65], v54
	v_add_f32_e32 v62, v62, v63
	v_pk_fma_f32 v[64:65], v[64:65], v[140:141], 0 op_sel_hi:[1,1,0]
	v_pk_fma_f32 v[64:65], v[68:69], v[142:143], v[64:65]
	v_cvt_pk_f32_fp8_e32 v[68:69], v55
	v_cvt_pk_f32_fp8_sdwa v[54:55], v55 src0_sel:WORD_1
	v_add_f32_dpp v62, v62, v62 quad_perm:[1,0,3,2] row_mask:0xf bank_mask:0xf bound_ctrl:1
	v_pk_fma_f32 v[64:65], v[68:69], v[144:145], v[64:65]
	v_pk_fma_f32 v[54:55], v[54:55], v[146:147], v[64:65]
	v_cvt_pk_f32_fp8_e32 v[64:65], v56
	v_cvt_pk_f32_fp8_sdwa v[68:69], v56 src0_sel:WORD_1
	v_add_f32_dpp v62, v62, v62 quad_perm:[2,3,0,1] row_mask:0xf bank_mask:0xf bound_ctrl:1
	v_pk_fma_f32 v[54:55], v[64:65], v[148:149], v[54:55]
	v_cvt_pk_f32_fp8_e32 v[64:65], v57
	v_cvt_pk_f32_fp8_sdwa v[56:57], v57 src0_sel:WORD_1
	v_pk_fma_f32 v[54:55], v[68:69], v[152:153], v[54:55]
	v_mov_b32_dpp v63, v62 row_half_mirror row_mask:0xf bank_mask:0xf bound_ctrl:1
	v_pk_fma_f32 v[54:55], v[64:65], v[150:151], v[54:55]
	v_cvt_pk_f32_fp8_sdwa v[64:65], v46 src0_sel:WORD_1
	v_pk_fma_f32 v[54:55], v[56:57], v[154:155], v[54:55]
	v_cvt_pk_f32_fp8_e32 v[56:57], v46
	v_add_f32_e32 v54, v54, v55
	v_pk_fma_f32 v[56:57], v[56:57], v[140:141], 0 op_sel_hi:[1,1,0]
	v_pk_fma_f32 v[56:57], v[64:65], v[142:143], v[56:57]
	v_cvt_pk_f32_fp8_e32 v[64:65], v47
	v_cvt_pk_f32_fp8_sdwa v[46:47], v47 src0_sel:WORD_1
	v_add_f32_dpp v54, v54, v54 quad_perm:[1,0,3,2] row_mask:0xf bank_mask:0xf bound_ctrl:1
	v_pk_fma_f32 v[56:57], v[64:65], v[144:145], v[56:57]
	v_pk_fma_f32 v[46:47], v[46:47], v[146:147], v[56:57]
	v_cvt_pk_f32_fp8_e32 v[56:57], v48
	v_cvt_pk_f32_fp8_sdwa v[64:65], v48 src0_sel:WORD_1
	v_add_f32_dpp v54, v54, v54 quad_perm:[2,3,0,1] row_mask:0xf bank_mask:0xf bound_ctrl:1
	v_pk_fma_f32 v[46:47], v[56:57], v[148:149], v[46:47]
	v_cvt_pk_f32_fp8_e32 v[56:57], v49
	v_cvt_pk_f32_fp8_sdwa v[48:49], v49 src0_sel:WORD_1
	v_pk_fma_f32 v[46:47], v[64:65], v[152:153], v[46:47]
	v_mov_b32_dpp v55, v54 row_half_mirror row_mask:0xf bank_mask:0xf bound_ctrl:1
	v_pk_fma_f32 v[46:47], v[56:57], v[150:151], v[46:47]
	v_cvt_pk_f32_fp8_sdwa v[56:57], v38 src0_sel:WORD_1
	v_pk_fma_f32 v[46:47], v[48:49], v[154:155], v[46:47]
	v_cvt_pk_f32_fp8_e32 v[48:49], v38
	v_add_f32_e32 v46, v46, v47
	v_pk_fma_f32 v[48:49], v[48:49], v[140:141], 0 op_sel_hi:[1,1,0]
	v_pk_fma_f32 v[48:49], v[56:57], v[142:143], v[48:49]
	v_cvt_pk_f32_fp8_e32 v[56:57], v39
	v_cvt_pk_f32_fp8_sdwa v[38:39], v39 src0_sel:WORD_1
	v_add_f32_dpp v46, v46, v46 quad_perm:[1,0,3,2] row_mask:0xf bank_mask:0xf bound_ctrl:1
	v_pk_fma_f32 v[48:49], v[56:57], v[144:145], v[48:49]
	v_pk_fma_f32 v[38:39], v[38:39], v[146:147], v[48:49]
	v_cvt_pk_f32_fp8_e32 v[48:49], v40
	v_cvt_pk_f32_fp8_sdwa v[56:57], v40 src0_sel:WORD_1
	v_add_f32_dpp v46, v46, v46 quad_perm:[2,3,0,1] row_mask:0xf bank_mask:0xf bound_ctrl:1
	v_pk_fma_f32 v[38:39], v[48:49], v[148:149], v[38:39]
	v_cvt_pk_f32_fp8_e32 v[48:49], v41
	v_cvt_pk_f32_fp8_sdwa v[40:41], v41 src0_sel:WORD_1
	v_pk_fma_f32 v[38:39], v[56:57], v[152:153], v[38:39]
	v_mov_b32_dpp v47, v46 row_half_mirror row_mask:0xf bank_mask:0xf bound_ctrl:1
	v_pk_fma_f32 v[38:39], v[48:49], v[150:151], v[38:39]
	s_waitcnt vmcnt(20)
	v_cvt_pk_f32_fp8_sdwa v[48:49], v30 src0_sel:WORD_1
	v_pk_fma_f32 v[38:39], v[40:41], v[154:155], v[38:39]
	v_cvt_pk_f32_fp8_e32 v[40:41], v30
	v_add_f32_e32 v38, v38, v39
	v_pk_fma_f32 v[40:41], v[40:41], v[140:141], 0 op_sel_hi:[1,1,0]
	v_pk_fma_f32 v[40:41], v[48:49], v[142:143], v[40:41]
	v_cvt_pk_f32_fp8_e32 v[48:49], v31
	v_cvt_pk_f32_fp8_sdwa v[30:31], v31 src0_sel:WORD_1
	v_add_f32_dpp v38, v38, v38 quad_perm:[1,0,3,2] row_mask:0xf bank_mask:0xf bound_ctrl:1
	v_pk_fma_f32 v[40:41], v[48:49], v[144:145], v[40:41]
	v_pk_fma_f32 v[30:31], v[30:31], v[146:147], v[40:41]
	v_cvt_pk_f32_fp8_e32 v[40:41], v32
	v_cvt_pk_f32_fp8_sdwa v[48:49], v32 src0_sel:WORD_1
	v_add_f32_dpp v38, v38, v38 quad_perm:[2,3,0,1] row_mask:0xf bank_mask:0xf bound_ctrl:1
	v_pk_fma_f32 v[30:31], v[40:41], v[148:149], v[30:31]
	v_cvt_pk_f32_fp8_e32 v[40:41], v33
	v_cvt_pk_f32_fp8_sdwa v[32:33], v33 src0_sel:WORD_1
	v_pk_fma_f32 v[30:31], v[48:49], v[152:153], v[30:31]
	v_mov_b32_dpp v39, v38 row_half_mirror row_mask:0xf bank_mask:0xf bound_ctrl:1
	v_pk_fma_f32 v[30:31], v[40:41], v[150:151], v[30:31]
	v_pk_fma_f32 v[30:31], v[32:33], v[154:155], v[30:31]
	s_nop 0
	v_add_f32_e32 v30, v30, v31
	s_nop 1
	v_add_f32_dpp v30, v30, v30 quad_perm:[1,0,3,2] row_mask:0xf bank_mask:0xf bound_ctrl:1
	s_nop 1
	v_add_f32_dpp v31, v30, v30 quad_perm:[2,3,0,1] row_mask:0xf bank_mask:0xf bound_ctrl:1
	v_add_u32_e32 v30, s69, v174
	v_cmp_gt_i32_e64 s[56:57], s10, v30
	v_mov_b32_dpp v32, v31 row_half_mirror row_mask:0xf bank_mask:0xf bound_ctrl:1
	s_and_saveexec_b64 s[6:7], s[56:57]
	s_cbranch_execz .LBB0_1640
	v_add_f32_e32 v33, v46, v47
	v_add_f32_e32 v46, v82, v83
	v_add_f32_e32 v41, v74, v75
	v_cndmask_b32_e32 v46, 0, v46, vcc
	v_add_f32_e32 v47, v126, v127
	v_add_f32_e32 v40, v66, v67
	v_cndmask_b32_e64 v41, v46, v41, s[42:43]
	v_add_f32_e32 v46, v122, v123
	v_cndmask_b32_e32 v47, 0, v47, vcc
	v_add_f32_e32 v31, v31, v32
	v_add_f32_e32 v32, v38, v39
	v_add_f32_e32 v39, v62, v63
	v_cndmask_b32_e64 v40, v41, v40, s[44:45]
	v_add_f32_e32 v41, v118, v119
	v_cndmask_b32_e64 v46, v47, v46, s[42:43]
	v_add_f32_e32 v38, v54, v55
	v_cndmask_b32_e64 v39, v40, v39, s[46:47]
	v_add_f32_e32 v40, v114, v115
	v_cndmask_b32_e64 v41, v46, v41, s[44:45]
	v_cndmask_b32_e64 v38, v39, v38, s[48:49]
	v_add_f32_e32 v39, v110, v111
	v_cndmask_b32_e64 v40, v41, v40, s[46:47]
	v_cndmask_b32_e64 v33, v38, v33, s[50:51]
	v_add_f32_e32 v38, v102, v103
	v_cndmask_b32_e64 v39, v40, v39, s[48:49]
	v_cndmask_b32_e64 v32, v33, v32, s[52:53]
	v_add_f32_e32 v33, v94, v95
	v_cndmask_b32_e64 v38, v39, v38, s[50:51]
	v_cndmask_b32_e64 v32, v32, v31, s[54:55]
	v_add_f32_e32 v31, v90, v91
	v_cndmask_b32_e64 v33, v38, v33, s[52:53]
	v_cndmask_b32_e64 v33, v33, v31, s[54:55]
	v_ashrrev_i32_e32 v31, 31, v30
	v_lshlrev_b64 v[30:31], 11, v[30:31]
	v_lshl_add_u64 v[30:31], v[136:137], 0, v[30:31]
	v_cvt_pk_bf16_f32 v33, v33, s0
	v_cvt_pk_bf16_f32 v32, v32, s0
	global_store_short v[30:31], v33, off
	global_store_short v[30:31], v32, off offset:16
	s_branch .LBB0_1640
